# gate/up rstd table: all unit loads issued before the first wait
# speedup vs baseline: 1.0225x; 1.0065x over previous
; #define LAS __attribute__((address_space(3)))
; __device__ __forceinline__ float fx_get(const i64* p) { return (float)(*p) * FXI; }
;     __host__ __device__ bool next(int i, Unit& u) const {
;         const long L = (long)i * G + c; if (L >= nwg) return false;
;         int wgid = (int)L; { constexpr int q = nwg / NXCD, r = nwg % NXCD; const int xcd = wgid % NXCD, off = wgid / NXCD; wgid = (xcd < r ? xcd * (q + 1) : r * (q + 1) + (xcd - r) * q) + off; }
;         const int gid = wgid / nig, fm = gid * WGM, w = wgid % nig;
;         u.pm = fm + (w % gsz); u.pn = w / gsz; return true;
;     }
; template <bool BY_COL, class Sched> __device__ __forceinline__ void stage_rstd(LAS unsigned char* lds, const Sched& S, const i64* ssq) {
;     LAS float* rsl = (LAS float*)(lds + RSL_OFF); const int tid = threadIdx.x;
; #pragma unroll 1
;     for (int i = 0; i < RSL_UNITS; ++i) { Unit u; if (!S.next(i, u)) break;
;         if (tid < 256) rsl[i * 256 + tid] = __builtin_amdgcn_rsqf(fx_get(ssq + (BY_COL ? u.pn : u.pm) * 256 + tid) * (1.0f / DM) + EPS); }
;     __syncthreads();
.LBB0_199:
	s_andn2_b64 vcc, exec, s[28:29]
	s_cbranch_vccnz .LBB0_443
	v_readlane_b32 s6, v252, 51
	v_readlane_b32 s7, v252, 52
	s_waitcnt lgkmcnt(0)
	s_mov_b64 s[30:31], s[94:95]
	s_lshl_b64 s[6:7], s[6:7], 3
	s_add_u32 s4, s30, s6
	s_addc_u32 s6, s31, s7
	s_lshl_b32 s5, s5, 17
	s_add_u32 s4, s4, s5
	s_addc_u32 s5, s6, 0
	v_mov_b32_e32 v215, v1
	v_lshl_add_u64 v[2:3], s[4:5], 0, v[214:215]
	s_movk_i32 s4, 0xe800
	s_mov_b64 s[28:29], s[2:3]
	s_and_saveexec_b64 s[42:43], s[38:39]
	s_mov_b32 s4, 0
	v_cmp_gt_i64_e32 vcc, s[28:29], v[216:217]
	s_cbranch_vccnz .Lrs_issued
	s_ashr_i32 s5, s28, 31
	s_lshr_b32 s5, s5, 29
	s_add_i32 s5, s28, s5
	s_ashr_i32 s6, s5, 3
	s_and_b32 s5, s5, -8
	s_sub_i32 s5, s28, s5
	s_cmp_lt_i32 s5, 0
	s_movk_i32 s7, 0xb1
	s_cselect_b32 s7, s7, 0xb0
	s_mul_i32 s5, s7, s5
	s_add_i32 s5, s5, s6
	s_mul_hi_i32 s6, s5, 0x2e8ba2e9
	s_lshr_b32 s7, s6, 31
	s_ashr_i32 s6, s6, 5
	s_add_i32 s6, s6, s7
	s_mul_i32 s7, s6, 0xb0
	s_sub_i32 s5, s5, s7
	s_bfe_u32 s7, s5, 0x3001c
	s_add_i32 s7, s5, s7
	s_and_b32 s7, s7, 0xfff8
	s_sub_i32 s5, s5, s7
	s_sext_i32_i16 s5, s5
	s_lshl_b32 s6, s6, 11
	s_lshl_b32 s5, s5, 8
	s_add_i32 s6, s5, s6
	s_ashr_i32 s7, s6, 31
	v_lshl_add_u64 v[4:5], s[6:7], 3, v[2:3]
	global_load_dwordx2 v[4:5], v[4:5], off
	s_add_i32 s4, s4, 1
	s_add_u32 s28, s28, s70
	s_addc_u32 s29, s29, s61
	v_cmp_gt_i64_e32 vcc, s[28:29], v[216:217]
	s_cbranch_vccnz .Lrs_issued
	s_ashr_i32 s5, s28, 31
	s_lshr_b32 s5, s5, 29
	s_add_i32 s5, s28, s5
	s_ashr_i32 s6, s5, 3
	s_and_b32 s5, s5, -8
	s_sub_i32 s5, s28, s5
	s_cmp_lt_i32 s5, 0
	s_movk_i32 s7, 0xb1
	s_cselect_b32 s7, s7, 0xb0
	s_mul_i32 s5, s7, s5
	s_add_i32 s5, s5, s6
	s_mul_hi_i32 s6, s5, 0x2e8ba2e9
	s_lshr_b32 s7, s6, 31
	s_ashr_i32 s6, s6, 5
	s_add_i32 s6, s6, s7
	s_mul_i32 s7, s6, 0xb0
	s_sub_i32 s5, s5, s7
	s_bfe_u32 s7, s5, 0x3001c
	s_add_i32 s7, s5, s7
	s_and_b32 s7, s7, 0xfff8
	s_sub_i32 s5, s5, s7
	s_sext_i32_i16 s5, s5
	s_lshl_b32 s6, s6, 11
	s_lshl_b32 s5, s5, 8
	s_add_i32 s6, s5, s6
	s_ashr_i32 s7, s6, 31
	v_lshl_add_u64 v[6:7], s[6:7], 3, v[2:3]
	global_load_dwordx2 v[6:7], v[6:7], off
	s_add_i32 s4, s4, 1
	s_add_u32 s28, s28, s70
	s_addc_u32 s29, s29, s61
	v_cmp_gt_i64_e32 vcc, s[28:29], v[216:217]
	s_cbranch_vccnz .Lrs_issued
	s_ashr_i32 s5, s28, 31
	s_lshr_b32 s5, s5, 29
	s_add_i32 s5, s28, s5
	s_ashr_i32 s6, s5, 3
	s_and_b32 s5, s5, -8
	s_sub_i32 s5, s28, s5
	s_cmp_lt_i32 s5, 0
	s_movk_i32 s7, 0xb1
	s_cselect_b32 s7, s7, 0xb0
	s_mul_i32 s5, s7, s5
	s_add_i32 s5, s5, s6
	s_mul_hi_i32 s6, s5, 0x2e8ba2e9
	s_lshr_b32 s7, s6, 31
	s_ashr_i32 s6, s6, 5
	s_add_i32 s6, s6, s7
	s_mul_i32 s7, s6, 0xb0
	s_sub_i32 s5, s5, s7
	s_bfe_u32 s7, s5, 0x3001c
	s_add_i32 s7, s5, s7
	s_and_b32 s7, s7, 0xfff8
	s_sub_i32 s5, s5, s7
	s_sext_i32_i16 s5, s5
	s_lshl_b32 s6, s6, 11
	s_lshl_b32 s5, s5, 8
	s_add_i32 s6, s5, s6
	s_ashr_i32 s7, s6, 31
	v_lshl_add_u64 v[8:9], s[6:7], 3, v[2:3]
	global_load_dwordx2 v[8:9], v[8:9], off
	s_add_i32 s4, s4, 1
	s_add_u32 s28, s28, s70
	s_addc_u32 s29, s29, s61
	v_cmp_gt_i64_e32 vcc, s[28:29], v[216:217]
	s_cbranch_vccnz .Lrs_issued
	s_ashr_i32 s5, s28, 31
	s_lshr_b32 s5, s5, 29
	s_add_i32 s5, s28, s5
	s_ashr_i32 s6, s5, 3
	s_and_b32 s5, s5, -8
	s_sub_i32 s5, s28, s5
	s_cmp_lt_i32 s5, 0
	s_movk_i32 s7, 0xb1
	s_cselect_b32 s7, s7, 0xb0
	s_mul_i32 s5, s7, s5
	s_add_i32 s5, s5, s6
	s_mul_hi_i32 s6, s5, 0x2e8ba2e9
	s_lshr_b32 s7, s6, 31
	s_ashr_i32 s6, s6, 5
	s_add_i32 s6, s6, s7
	s_mul_i32 s7, s6, 0xb0
	s_sub_i32 s5, s5, s7
	s_bfe_u32 s7, s5, 0x3001c
	s_add_i32 s7, s5, s7
	s_and_b32 s7, s7, 0xfff8
	s_sub_i32 s5, s5, s7
	s_sext_i32_i16 s5, s5
	s_lshl_b32 s6, s6, 11
	s_lshl_b32 s5, s5, 8
	s_add_i32 s6, s5, s6
	s_ashr_i32 s7, s6, 31
	v_lshl_add_u64 v[10:11], s[6:7], 3, v[2:3]
	global_load_dwordx2 v[10:11], v[10:11], off
	s_add_i32 s4, s4, 1
	s_add_u32 s28, s28, s70
	s_addc_u32 s29, s29, s61
	v_cmp_gt_i64_e32 vcc, s[28:29], v[216:217]
	s_cbranch_vccnz .Lrs_issued
	s_ashr_i32 s5, s28, 31
	s_lshr_b32 s5, s5, 29
	s_add_i32 s5, s28, s5
	s_ashr_i32 s6, s5, 3
	s_and_b32 s5, s5, -8
	s_sub_i32 s5, s28, s5
	s_cmp_lt_i32 s5, 0
	s_movk_i32 s7, 0xb1
	s_cselect_b32 s7, s7, 0xb0
	s_mul_i32 s5, s7, s5
	s_add_i32 s5, s5, s6
	s_mul_hi_i32 s6, s5, 0x2e8ba2e9
	s_lshr_b32 s7, s6, 31
	s_ashr_i32 s6, s6, 5
	s_add_i32 s6, s6, s7
	s_mul_i32 s7, s6, 0xb0
	s_sub_i32 s5, s5, s7
	s_bfe_u32 s7, s5, 0x3001c
	s_add_i32 s7, s5, s7
	s_and_b32 s7, s7, 0xfff8
	s_sub_i32 s5, s5, s7
	s_sext_i32_i16 s5, s5
	s_lshl_b32 s6, s6, 11
	s_lshl_b32 s5, s5, 8
	s_add_i32 s6, s5, s6
	s_ashr_i32 s7, s6, 31
	v_lshl_add_u64 v[12:13], s[6:7], 3, v[2:3]
	global_load_dwordx2 v[12:13], v[12:13], off
	s_add_i32 s4, s4, 1
	s_add_u32 s28, s28, s70
	s_addc_u32 s29, s29, s61
	v_cmp_gt_i64_e32 vcc, s[28:29], v[216:217]
	s_cbranch_vccnz .Lrs_issued
	s_ashr_i32 s5, s28, 31
	s_lshr_b32 s5, s5, 29
	s_add_i32 s5, s28, s5
	s_ashr_i32 s6, s5, 3
	s_and_b32 s5, s5, -8
	s_sub_i32 s5, s28, s5
	s_cmp_lt_i32 s5, 0
	s_movk_i32 s7, 0xb1
	s_cselect_b32 s7, s7, 0xb0
	s_mul_i32 s5, s7, s5
	s_add_i32 s5, s5, s6
	s_mul_hi_i32 s6, s5, 0x2e8ba2e9
	s_lshr_b32 s7, s6, 31
	s_ashr_i32 s6, s6, 5
	s_add_i32 s6, s6, s7
	s_mul_i32 s7, s6, 0xb0
	s_sub_i32 s5, s5, s7
	s_bfe_u32 s7, s5, 0x3001c
	s_add_i32 s7, s5, s7
	s_and_b32 s7, s7, 0xfff8
	s_sub_i32 s5, s5, s7
	s_sext_i32_i16 s5, s5
	s_lshl_b32 s6, s6, 11
	s_lshl_b32 s5, s5, 8
	s_add_i32 s6, s5, s6
	s_ashr_i32 s7, s6, 31
	v_lshl_add_u64 v[14:15], s[6:7], 3, v[2:3]
	global_load_dwordx2 v[14:15], v[14:15], off
	s_add_i32 s4, s4, 1
; __device__ __forceinline__ float fx_get(const i64* p) { return (float)(*p) * FXI; }
; template <bool BY_COL, class Sched> __device__ __forceinline__ void stage_rstd(LAS unsigned char* lds, const Sched& S, const i64* ssq) {
;     ...
;     for (int i = 0; i < RSL_UNITS; ++i) { Unit u; if (!S.next(i, u)) break;
;         if (tid < 256) rsl[i * 256 + tid] = __builtin_amdgcn_rsqf(fx_get(ssq + (BY_COL ? u.pn : u.pm) * 256 + tid) * (1.0f / DM) + EPS); }
;     __syncthreads();
.Lrs_issued:
	s_waitcnt vmcnt(0)
	s_cmp_le_u32 s4, 0
	s_cbranch_scc1 .Lrs_done
	v_xor_b32_e32 v0, v4, v5
	v_ffbh_i32_e32 v16, v5
	v_ashrrev_i32_e32 v0, 31, v0
	v_add_u32_e32 v0, 32, v0
	v_add_u32_e32 v16, -1, v16
	v_min_u32_e32 v0, v16, v0
	v_lshlrev_b64 v[4:5], v0, v[4:5]
	v_min_u32_e32 v4, 1, v4
	v_or_b32_e32 v4, v5, v4
	v_cvt_f32_i32_e32 v4, v4
	v_sub_u32_e32 v0, 32, v0
	v_ldexp_f32 v0, v4, v0
	v_mul_f32_e32 v0, 0x33800000, v0
	v_fmamk_f32 v0, v0, 0x3a800000, v213
	v_rsq_f32_e32 v0, v0
	s_nop 0
	ds_write_b32 v211, v0
	s_cmp_le_u32 s4, 1
	s_cbranch_scc1 .Lrs_done
	v_xor_b32_e32 v0, v6, v7
	v_ffbh_i32_e32 v16, v7
	v_ashrrev_i32_e32 v0, 31, v0
	v_add_u32_e32 v0, 32, v0
	v_add_u32_e32 v16, -1, v16
	v_min_u32_e32 v0, v16, v0
	v_lshlrev_b64 v[6:7], v0, v[6:7]
	v_min_u32_e32 v6, 1, v6
	v_or_b32_e32 v6, v7, v6
	v_cvt_f32_i32_e32 v6, v6
	v_sub_u32_e32 v0, 32, v0
	v_ldexp_f32 v0, v6, v0
	v_mul_f32_e32 v0, 0x33800000, v0
	v_fmamk_f32 v0, v0, 0x3a800000, v213
	v_rsq_f32_e32 v0, v0
	s_nop 0
	ds_write_b32 v211, v0 offset:1024
	s_cmp_le_u32 s4, 2
	s_cbranch_scc1 .Lrs_done
	v_xor_b32_e32 v0, v8, v9
	v_ffbh_i32_e32 v16, v9
	v_ashrrev_i32_e32 v0, 31, v0
	v_add_u32_e32 v0, 32, v0
	v_add_u32_e32 v16, -1, v16
	v_min_u32_e32 v0, v16, v0
	v_lshlrev_b64 v[8:9], v0, v[8:9]
	v_min_u32_e32 v8, 1, v8
	v_or_b32_e32 v8, v9, v8
	v_cvt_f32_i32_e32 v8, v8
	v_sub_u32_e32 v0, 32, v0
	v_ldexp_f32 v0, v8, v0
	v_mul_f32_e32 v0, 0x33800000, v0
	v_fmamk_f32 v0, v0, 0x3a800000, v213
	v_rsq_f32_e32 v0, v0
	s_nop 0
	ds_write_b32 v211, v0 offset:2048
	s_cmp_le_u32 s4, 3
	s_cbranch_scc1 .Lrs_done
	v_xor_b32_e32 v0, v10, v11
	v_ffbh_i32_e32 v16, v11
	v_ashrrev_i32_e32 v0, 31, v0
	v_add_u32_e32 v0, 32, v0
	v_add_u32_e32 v16, -1, v16
	v_min_u32_e32 v0, v16, v0
	v_lshlrev_b64 v[10:11], v0, v[10:11]
	v_min_u32_e32 v10, 1, v10
	v_or_b32_e32 v10, v11, v10
	v_cvt_f32_i32_e32 v10, v10
	v_sub_u32_e32 v0, 32, v0
	v_ldexp_f32 v0, v10, v0
	v_mul_f32_e32 v0, 0x33800000, v0
	v_fmamk_f32 v0, v0, 0x3a800000, v213
	v_rsq_f32_e32 v0, v0
	s_nop 0
	ds_write_b32 v211, v0 offset:3072
	s_cmp_le_u32 s4, 4
	s_cbranch_scc1 .Lrs_done
	v_xor_b32_e32 v0, v12, v13
	v_ffbh_i32_e32 v16, v13
	v_ashrrev_i32_e32 v0, 31, v0
	v_add_u32_e32 v0, 32, v0
	v_add_u32_e32 v16, -1, v16
	v_min_u32_e32 v0, v16, v0
	v_lshlrev_b64 v[12:13], v0, v[12:13]
	v_min_u32_e32 v12, 1, v12
	v_or_b32_e32 v12, v13, v12
	v_cvt_f32_i32_e32 v12, v12
	v_sub_u32_e32 v0, 32, v0
	v_ldexp_f32 v0, v12, v0
	v_mul_f32_e32 v0, 0x33800000, v0
	v_fmamk_f32 v0, v0, 0x3a800000, v213
	v_rsq_f32_e32 v0, v0
	s_nop 0
	ds_write_b32 v211, v0 offset:4096
	s_cmp_le_u32 s4, 5
	s_cbranch_scc1 .Lrs_done
	v_xor_b32_e32 v0, v14, v15
	v_ffbh_i32_e32 v16, v15
	v_ashrrev_i32_e32 v0, 31, v0
	v_add_u32_e32 v0, 32, v0
	v_add_u32_e32 v16, -1, v16
	v_min_u32_e32 v0, v16, v0
	v_lshlrev_b64 v[14:15], v0, v[14:15]
	v_min_u32_e32 v14, 1, v14
	v_or_b32_e32 v14, v15, v14
	v_cvt_f32_i32_e32 v14, v14
	v_sub_u32_e32 v0, 32, v0
	v_ldexp_f32 v0, v14, v0
	v_mul_f32_e32 v0, 0x33800000, v0
	v_fmamk_f32 v0, v0, 0x3a800000, v213
	v_rsq_f32_e32 v0, v0
	s_nop 0
	ds_write_b32 v211, v0 offset:5120
.Lrs_done:
	s_or_b64 exec, exec, s[42:43]
; #define PG8_STAGE(bufoff, gbase, voff) do { _Pragma("unroll") for (int _i = 0; _i < 2; ++_i) \
;         __builtin_amdgcn_global_load_lds((const unsigned*)((const char*)(gbase) + (voff)[_i]), (PG8_LAS unsigned*)(lds + (bufoff) + ldsw + _i * 8192), 16, 0, 0); } while (0)
; #define PG8_BAR __builtin_amdgcn_s_barrier()
; template <class Epi, class Sched, bool ALIGN_EPI = false>
; __device__ __forceinline__ void gemm_phase(PG8_LAS unsigned char* lds, const Gemm g, const Sched& S, const Epi& E) {
;     ...
;     const int tid = tid_, wid = __builtin_amdgcn_readfirstlane(tid >> 6), lane = tid & 63, wr = wid >> 2, wc = wid & 3, fr = lane & 15, fq = lane >> 4;
;     const int K = g.K, nt = K / BK;
;     unsigned voffA[2], voffB[2];
; #pragma unroll
;     for (int i = 0; i < 2; ++i) { int R, C; stage_rc(tid * 16 + i * 8192, R, C); const int Rb = Epi::PERM ? ((R & ~31) + perm32(R & 31)) : R;
;         voffA[i] = (unsigned)(R * K + C) * 2u; voffB[i] = (unsigned)(Rb * K + C) * 2u; }
;     const size_t kstep = (size_t)(BK * 2);
;     const size_t hstep = (size_t)HALF * K * 2;
;     const size_t tstep = 2 * hstep;
;     const unsigned ldsw = (unsigned)wid * 1024u;
;     const int aoff = lds_byte(wr * 64 + fr, fq * 8), boff = lds_byte(wc * 32 + fr, fq * 8);
;     ...
;     Unit cur, nxt; int ui = 0;
;     if (!S.next(0, cur)) return;
;     f32x4 acc[2][2][4][2];
; #pragma unroll
;     for (int a = 0; a < 2; ++a)
; #pragma unroll
;         for (int b = 0; b < 2; ++b)
; #pragma unroll
;             for (int m = 0; m < 4; ++m)
; #pragma unroll
;                 for (int n = 0; n < 2; ++n) acc[a][b][m][n] = (f32x4){0.f, 0.f, 0.f, 0.f};
;     bf16x8 At[4][2], B0[2][2], B1[2][2];
;     const char* cA = (const char*)g.A + (size_t)cur.pm * tstep; const char* cB = (const char*)g.Bt + (size_t)cur.pn * tstep;
;     {
;         PG8_STAGE(PG8_SB(0, 0), cB, voffB); PG8_STAGE(PG8_SB(0, 1), cB + hstep, voffB); PG8_STAGE(PG8_SA(0, 0), cA, voffA); PG8_STAGE(PG8_SA(0, 1), cA + hstep, voffA);
;         if (wr == 1) PG8_BAR;
.LBB0_206:
	v_readlane_b32 s4, v252, 61
	v_mov_b32_e32 v16, v210
	v_readlane_b32 s5, v252, 62
	s_waitcnt lgkmcnt(0)
	s_barrier
	s_andn2_b64 vcc, exec, s[4:5]
	v_readfirstlane_b32 s4, v16
	s_cbranch_vccnz .LBB0_222
	v_lshlrev_b32_e32 v0, 4, v16
	v_add_u32_e32 v2, 0x2000, v0
	v_ashrrev_i32_e32 v3, 31, v2
	v_lshrrev_b32_e32 v3, 22, v3
	v_add_u32_e32 v3, v2, v3
	v_ashrrev_i32_e32 v10, 10, v3
	v_mul_i32_i24_e32 v3, 0x400, v10
	v_sub_u32_e32 v2, v2, v3
	s_ashr_i32 s15, s4, 6
	v_lshrrev_b32_e32 v3, 4, v2
	s_ashr_i32 s5, s4, 8
	s_lshl_b32 s6, s15, 10
	v_readlane_b32 s7, v254, 40
	v_bitop3_b32 v2, v3, v2, 32 bitop3:0x6c
	s_add_u32 s9, s30, s7
	v_ashrrev_i32_e32 v3, 31, v2
	s_addc_u32 s12, s31, 0
	v_lshrrev_b32_e32 v3, 26, v3
	s_add_u32 s7, s30, 0xa400000
	v_readlane_b32 s10, v252, 23
	v_add_u32_e32 v3, v2, v3
	v_lshlrev_b32_e32 v4, 3, v10
	s_addc_u32 s8, s31, 0
	v_readlane_b32 s11, v252, 24
	v_ashrrev_i32_e32 v11, 6, v3
	v_and_b32_e32 v4, -16, v4
	s_and_b64 s[10:11], s[10:11], exec
	v_add_u32_e32 v4, v11, v4
	v_and_b32_e32 v5, 3, v11
	s_mov_b32 s11, 0x1fffe0
	v_lshrrev_b32_e32 v6, 2, v4
	v_lshlrev_b32_e32 v7, 1, v4
	v_and_or_b32 v5, v4, s11, v5
	v_and_b32_e32 v6, 4, v6
	v_and_b32_e32 v7, 24, v7
	v_and_b32_e32 v3, 0xc0, v3
	v_or3_b32 v5, v5, v6, v7
	v_sub_u32_e32 v2, v2, v3
	v_mov_b32_e32 v7, 1
	v_lshlrev_b32_e32 v6, 5, v10
	v_ashrrev_i16_sdwa v2, v7, sext(v2) dst_sel:DWORD dst_unused:UNUSED_PAD src0_sel:DWORD src1_sel:BYTE_0
	v_and_b32_e32 v6, 32, v6
	v_bfe_i32 v12, v2, 0, 16
	v_add_lshl_u32 v2, v6, v12, 1
	v_lshl_add_u32 v130, v5, 11, v2
	v_lshl_add_u32 v132, v4, 11, v2
	v_bfe_i32 v2, v16, 27, 1
	v_lshrrev_b32_e32 v2, 22, v2
	v_add_u32_e32 v2, v0, v2
	v_and_b32_e32 v2, 0xfffffc00, v2
	v_sub_u32_e32 v0, v0, v2
	v_lshrrev_b32_e32 v2, 4, v0
	v_ashrrev_i32_e32 v3, 31, v16
	v_bitop3_b32 v0, v2, v0, 32 bitop3:0x6c
	v_lshrrev_b32_e32 v3, 26, v3
	v_ashrrev_i32_e32 v2, 31, v0
	v_add_u32_e32 v3, v16, v3
	v_lshrrev_b32_e32 v2, 26, v2
	v_ashrrev_i32_e32 v14, 6, v3
	v_add_u32_e32 v2, v0, v2
	v_lshlrev_b32_e32 v3, 3, v14
	s_cselect_b32 s10, 0x1780000, 0
	v_ashrrev_i32_e32 v13, 6, v2
	v_and_b32_e32 v3, -16, v3
	s_add_u32 s9, s9, s10
	v_add_u32_e32 v3, v13, v3
	s_addc_u32 s10, s12, 0
	v_and_b32_e32 v4, 3, v13
	v_lshrrev_b32_e32 v5, 2, v3
	v_lshlrev_b32_e32 v6, 1, v3
	v_and_b32_e32 v2, 0xc0, v2
	s_add_u32 s9, s9, 0x400000
	v_and_or_b32 v4, v3, s11, v4
	v_and_b32_e32 v5, 4, v5
	v_and_b32_e32 v6, 24, v6
	v_sub_u32_e32 v0, v0, v2
	s_addc_u32 s10, s10, 0
	v_or3_b32 v4, v4, v5, v6
	v_lshlrev_b32_e32 v5, 5, v14
	v_ashrrev_i16_sdwa v0, v7, sext(v0) dst_sel:DWORD dst_unused:UNUSED_PAD src0_sel:DWORD src1_sel:BYTE_0
	v_readlane_b32 s12, v253, 4
	v_and_b32_e32 v5, 32, v5
	v_bfe_i32 v15, v0, 0, 16
	v_readlane_b32 s13, v253, 5
	s_add_u32 s54, s9, s12
	v_add_lshl_u32 v2, v5, v15, 1
	s_addc_u32 s55, s10, s13
	s_add_i32 s11, s6, 0
	v_lshl_add_u32 v0, v4, 11, v2
	s_add_i32 m0, s11, 0x10000
	v_lshl_add_u32 v134, v3, 11, v2
	global_load_lds_dwordx4 v0, s[54:55]
	s_add_i32 m0, s11, 0x12000
	s_add_u32 s12, s54, 0x40000
	global_load_lds_dwordx4 v130, s[54:55]
	s_addc_u32 s13, s55, 0
	s_add_i32 m0, s11, 0x14000
	v_mov_b32_e32 v131, v1
	global_load_lds_dwordx4 v0, s[12:13]
	s_add_i32 m0, s11, 0x16000
	v_mov_b32_e32 v135, v1
	global_load_lds_dwordx4 v130, s[12:13]
	v_readlane_b32 s12, v253, 2
	v_readlane_b32 s13, v253, 3
	s_add_u32 s76, s7, s12
	s_addc_u32 s77, s8, s13
	s_add_i32 s12, s11, 0x2000
	s_mov_b32 m0, s11
	s_add_u32 s16, s76, 0x40000
	global_load_lds_dwordx4 v134, s[76:77]
	s_mov_b32 m0, s12
	s_addc_u32 s17, s77, 0
	s_add_i32 s13, s11, 0x4000
	global_load_lds_dwordx4 v132, s[76:77]
	s_mov_b32 m0, s13
	s_add_i32 s14, s11, 0x6000
	global_load_lds_dwordx4 v134, s[16:17]
	s_mov_b32 m0, s14
	v_mov_b32_e32 v133, v1
	global_load_lds_dwordx4 v132, s[16:17]
	s_cmp_eq_u32 s5, 1
	v_mov_b32_e32 v251, 1
	v_lshl_add_u64 v[8:9], s[54:55], 0, v[0:1]
	v_lshl_add_u64 v[6:7], s[54:55], 0, v[130:131]
	v_lshl_add_u64 v[2:3], s[76:77], 0, v[134:135]
	s_cselect_b64 s[28:29], -1, 0
	s_cmp_lg_u32 s5, 1
	v_lshl_add_u64 v[4:5], s[76:77], 0, v[132:133]
	s_cbranch_scc1 .LBB0_209
	s_barrier
